# PEER top-k head loop: all 16 operand loads (sub-keys + query pieces) requested one head ahead into free registers, staged/copied at the head top
# baseline (speedup 1.0000x reference)
.LBB0_1345:
	s_movk_i32 s81, 0x80
	s_lshl_b32 s0, s48, 7
	s_mov_b32 s80, s48
	s_add_i32 s48, s0, s62
	v_or_b32_e32 v0, s48, v171
	v_ashrrev_i32_e32 v1, 31, v0
	v_lshlrev_b64 v[16:17], 10, v[0:1]
	v_lshlrev_b64 v[0:1], 11, v[0:1]
	v_lshl_add_u64 v[12:13], v[156:157], 0, v[0:1]
	v_mov_b64_e32 v[0:1], v[154:155]
	s_mov_b32 s33, s41
	s_mov_b32 s83, 0
	global_load_dwordx4 v[104:107], v[0:1], off
	s_mov_b32 s82, 0x2000
	v_lshl_add_u64 v[168:169], v[0:1], 0, s[82:83]
	global_load_dwordx4 v[108:111], v[168:169], off
	s_mov_b32 s82, 0x4000
	v_lshl_add_u64 v[168:169], v[0:1], 0, s[82:83]
	global_load_dwordx4 v[112:115], v[168:169], off
	s_mov_b32 s82, 0x6000
	v_lshl_add_u64 v[168:169], v[0:1], 0, s[82:83]
	global_load_dwordx4 v[116:119], v[168:169], off
	s_mov_b32 s82, 0x8000
	v_lshl_add_u64 v[168:169], v[0:1], 0, s[82:83]
	global_load_dwordx4 v[120:123], v[168:169], off
	s_mov_b32 s82, 0xa000
	v_lshl_add_u64 v[168:169], v[0:1], 0, s[82:83]
	global_load_dwordx4 v[124:127], v[168:169], off
	s_mov_b32 s82, 0xc000
	v_lshl_add_u64 v[168:169], v[0:1], 0, s[82:83]
	global_load_dwordx4 v[128:131], v[168:169], off
	s_mov_b32 s82, 0xe000
	v_lshl_add_u64 v[168:169], v[0:1], 0, s[82:83]
	global_load_dwordx4 v[132:135], v[168:169], off
	global_load_dwordx4 v[136:139], v[12:13], off
	global_load_dwordx4 v[140:143], v[12:13], off offset:64
	global_load_dwordx4 v[144:147], v[12:13], off offset:128
	global_load_dwordx4 v[220:223], v[12:13], off offset:192
	global_load_dwordx4 v[224:227], v[12:13], off offset:256
	global_load_dwordx4 v[228:231], v[12:13], off offset:320
	global_load_dwordx4 v[232:235], v[12:13], off offset:384
	global_load_dwordx4 v[236:239], v[12:13], off offset:448
.LBB0_1346:
	s_mov_b32 s78, 0x10001
	s_mov_b32 s79, 0x10001
	v_mov_b32_e32 v70, 0
	v_mov_b32_e32 v71, 0
	s_mov_b32 s40, 0
	s_waitcnt lgkmcnt(0)
	s_barrier
	s_waitcnt vmcnt(0)
	ds_write_b128 v208, v[104:107]
	ds_write_b128 v209, v[108:111]
	ds_write_b128 v210, v[112:115]
	ds_write_b128 v211, v[116:119]
	ds_write_b128 v212, v[120:123]
	ds_write_b128 v213, v[124:127]
	ds_write_b128 v214, v[128:131]
	ds_write_b128 v215, v[132:135]
	v_pk_mov_b32 v[50:51], v[136:137], v[136:137] op_sel:[0,1] op_sel_hi:[0,1]
	v_pk_mov_b32 v[52:53], v[138:139], v[138:139] op_sel:[0,1] op_sel_hi:[0,1]
	v_pk_mov_b32 v[54:55], v[140:141], v[140:141] op_sel:[0,1] op_sel_hi:[0,1]
	v_pk_mov_b32 v[56:57], v[142:143], v[142:143] op_sel:[0,1] op_sel_hi:[0,1]
	v_pk_mov_b32 v[58:59], v[144:145], v[144:145] op_sel:[0,1] op_sel_hi:[0,1]
	v_pk_mov_b32 v[60:61], v[146:147], v[146:147] op_sel:[0,1] op_sel_hi:[0,1]
	v_pk_mov_b32 v[62:63], v[220:221], v[220:221] op_sel:[0,1] op_sel_hi:[0,1]
	v_pk_mov_b32 v[64:65], v[222:223], v[222:223] op_sel:[0,1] op_sel_hi:[0,1]
	v_pk_mov_b32 v[12:13], v[224:225], v[224:225] op_sel:[0,1] op_sel_hi:[0,1]
	v_pk_mov_b32 v[14:15], v[226:227], v[226:227] op_sel:[0,1] op_sel_hi:[0,1]
	v_pk_mov_b32 v[8:9], v[228:229], v[228:229] op_sel:[0,1] op_sel_hi:[0,1]
	v_pk_mov_b32 v[10:11], v[230:231], v[230:231] op_sel:[0,1] op_sel_hi:[0,1]
	v_pk_mov_b32 v[4:5], v[232:233], v[232:233] op_sel:[0,1] op_sel_hi:[0,1]
	v_pk_mov_b32 v[6:7], v[234:235], v[234:235] op_sel:[0,1] op_sel_hi:[0,1]
	v_pk_mov_b32 v[0:1], v[236:237], v[236:237] op_sel:[0,1] op_sel_hi:[0,1]
	v_pk_mov_b32 v[2:3], v[238:239], v[238:239] op_sel:[0,1] op_sel_hi:[0,1]
	s_cmp_eq_u32 s33, 7
	s_cbranch_scc1 .Lmy_tpf_skip
	s_add_i32 s92, s33, 1
	s_lshl_b32 s96, s92, 16
	s_mov_b32 s97, 0
	v_lshl_add_u64 v[166:167], v[154:155], 0, s[96:97]
	s_cmp_lt_u32 s92, 4
	s_cselect_b32 s93, s3, s56
	s_cselect_b32 s76, s2, s55
	v_mov_b32_e32 v240, s76
	v_mov_b32_e32 v241, s93
	s_lshl_b32 s94, s92, 9
	s_and_b32 s94, s94, 0x600
	s_mov_b32 s95, 0
	v_lshl_add_u64 v[240:241], v[16:17], 1, v[240:241]
	v_lshl_add_u64 v[240:241], v[240:241], 0, s[94:95]
	v_lshl_add_u64 v[240:241], v[240:241], 0, v[148:149]
	s_mov_b32 s83, 0
	global_load_dwordx4 v[104:107], v[166:167], off
	s_mov_b32 s82, 0x2000
	v_lshl_add_u64 v[168:169], v[166:167], 0, s[82:83]
	global_load_dwordx4 v[108:111], v[168:169], off
	s_mov_b32 s82, 0x4000
	v_lshl_add_u64 v[168:169], v[166:167], 0, s[82:83]
	global_load_dwordx4 v[112:115], v[168:169], off
	s_mov_b32 s82, 0x6000
	v_lshl_add_u64 v[168:169], v[166:167], 0, s[82:83]
	global_load_dwordx4 v[116:119], v[168:169], off
	s_mov_b32 s82, 0x8000
	v_lshl_add_u64 v[168:169], v[166:167], 0, s[82:83]
	global_load_dwordx4 v[120:123], v[168:169], off
	s_mov_b32 s82, 0xa000
	v_lshl_add_u64 v[168:169], v[166:167], 0, s[82:83]
	global_load_dwordx4 v[124:127], v[168:169], off
	s_mov_b32 s82, 0xc000
	v_lshl_add_u64 v[168:169], v[166:167], 0, s[82:83]
	global_load_dwordx4 v[128:131], v[168:169], off
	s_mov_b32 s82, 0xe000
	v_lshl_add_u64 v[168:169], v[166:167], 0, s[82:83]
	global_load_dwordx4 v[132:135], v[168:169], off
	global_load_dwordx4 v[136:139], v[240:241], off
	global_load_dwordx4 v[140:143], v[240:241], off offset:64
	global_load_dwordx4 v[144:147], v[240:241], off offset:128
	global_load_dwordx4 v[220:223], v[240:241], off offset:192
	global_load_dwordx4 v[224:227], v[240:241], off offset:256
	global_load_dwordx4 v[228:231], v[240:241], off offset:320
	global_load_dwordx4 v[232:235], v[240:241], off offset:384
	global_load_dwordx4 v[236:239], v[240:241], off offset:448
.Lmy_tpf_skip:
	s_waitcnt lgkmcnt(0)
	s_barrier
	ds_read_b128 v[18:21], v184
	ds_read_b128 v[22:25], v184 offset:64
	s_waitcnt lgkmcnt(1)
	v_mfma_f32_16x16x32_bf16 v[18:21], v[50:53], v[18:21], 0
	s_waitcnt lgkmcnt(0)
	v_mfma_f32_16x16x32_bf16 v[18:21], v[54:57], v[22:25], v[18:21]
	ds_read_b128 v[22:25], v184 offset:128
	ds_read_b128 v[26:29], v184 offset:192
	s_waitcnt lgkmcnt(1)
	v_mfma_f32_16x16x32_bf16 v[18:21], v[58:61], v[22:25], v[18:21]
	s_waitcnt lgkmcnt(0)
	v_mfma_f32_16x16x32_bf16 v[18:21], v[62:65], v[26:29], v[18:21]
	ds_read_b128 v[22:25], v184 offset:4352
	ds_read_b128 v[26:29], v184 offset:4416
	s_waitcnt lgkmcnt(1)
	v_mfma_f32_16x16x32_bf16 v[22:25], v[50:53], v[22:25], 0
	s_waitcnt lgkmcnt(0)
	v_mfma_f32_16x16x32_bf16 v[22:25], v[54:57], v[26:29], v[22:25]
	ds_read_b128 v[26:29], v184 offset:4480
	ds_read_b128 v[30:33], v184 offset:4544
	s_waitcnt lgkmcnt(1)
	v_mfma_f32_16x16x32_bf16 v[22:25], v[58:61], v[26:29], v[22:25]
	s_waitcnt lgkmcnt(0)
	v_mfma_f32_16x16x32_bf16 v[22:25], v[62:65], v[30:33], v[22:25]
	ds_read_b128 v[26:29], v184 offset:8704
	ds_read_b128 v[30:33], v184 offset:8768
	s_waitcnt lgkmcnt(1)
	v_mfma_f32_16x16x32_bf16 v[26:29], v[50:53], v[26:29], 0
	s_waitcnt lgkmcnt(0)
	v_mfma_f32_16x16x32_bf16 v[26:29], v[54:57], v[30:33], v[26:29]
	ds_read_b128 v[30:33], v184 offset:8832
	ds_read_b128 v[34:37], v184 offset:8896
	s_waitcnt lgkmcnt(1)
	v_mfma_f32_16x16x32_bf16 v[26:29], v[58:61], v[30:33], v[26:29]
	s_waitcnt lgkmcnt(0)
	v_mfma_f32_16x16x32_bf16 v[26:29], v[62:65], v[34:37], v[26:29]
	ds_read_b128 v[30:33], v184 offset:13056
	ds_read_b128 v[34:37], v184 offset:13120
	s_waitcnt lgkmcnt(1)
	v_mfma_f32_16x16x32_bf16 v[30:33], v[50:53], v[30:33], 0
	s_waitcnt lgkmcnt(0)
	v_mfma_f32_16x16x32_bf16 v[30:33], v[54:57], v[34:37], v[30:33]
	ds_read_b128 v[34:37], v184 offset:13184
	ds_read_b128 v[38:41], v184 offset:13248
	s_waitcnt lgkmcnt(1)
	v_mfma_f32_16x16x32_bf16 v[30:33], v[58:61], v[34:37], v[30:33]
	s_waitcnt lgkmcnt(0)
	v_mfma_f32_16x16x32_bf16 v[30:33], v[62:65], v[38:41], v[30:33]
	ds_read_b128 v[34:37], v184 offset:17408
	ds_read_b128 v[38:41], v184 offset:17472
	s_waitcnt lgkmcnt(1)
	v_mfma_f32_16x16x32_bf16 v[34:37], v[50:53], v[34:37], 0
	s_waitcnt lgkmcnt(0)
	v_mfma_f32_16x16x32_bf16 v[34:37], v[54:57], v[38:41], v[34:37]
	ds_read_b128 v[38:41], v184 offset:17536
	ds_read_b128 v[42:45], v184 offset:17600
	s_waitcnt lgkmcnt(1)
	v_mfma_f32_16x16x32_bf16 v[34:37], v[58:61], v[38:41], v[34:37]
	s_waitcnt lgkmcnt(0)
	v_mfma_f32_16x16x32_bf16 v[34:37], v[62:65], v[42:45], v[34:37]
	ds_read_b128 v[38:41], v184 offset:21760
	ds_read_b128 v[42:45], v184 offset:21824
	s_waitcnt lgkmcnt(1)
	v_mfma_f32_16x16x32_bf16 v[38:41], v[50:53], v[38:41], 0
	s_waitcnt lgkmcnt(0)
	v_mfma_f32_16x16x32_bf16 v[38:41], v[54:57], v[42:45], v[38:41]
	ds_read_b128 v[42:45], v184 offset:21888
	ds_read_b128 v[46:49], v184 offset:21952
	s_waitcnt lgkmcnt(1)
	v_mfma_f32_16x16x32_bf16 v[38:41], v[58:61], v[42:45], v[38:41]
	s_waitcnt lgkmcnt(0)
	v_mfma_f32_16x16x32_bf16 v[38:41], v[62:65], v[46:49], v[38:41]
	ds_read_b128 v[42:45], v184 offset:26112
	ds_read_b128 v[46:49], v184 offset:26176
	s_waitcnt lgkmcnt(1)
	v_mfma_f32_16x16x32_bf16 v[42:45], v[50:53], v[42:45], 0
	s_waitcnt lgkmcnt(0)
	v_mfma_f32_16x16x32_bf16 v[42:45], v[54:57], v[46:49], v[42:45]
	ds_read_b128 v[46:49], v184 offset:26240
	ds_read_b128 v[66:69], v184 offset:26304
	s_waitcnt lgkmcnt(1)
	v_mfma_f32_16x16x32_bf16 v[42:45], v[58:61], v[46:49], v[42:45]
	s_waitcnt lgkmcnt(0)
	v_mfma_f32_16x16x32_bf16 v[42:45], v[62:65], v[66:69], v[42:45]
	ds_read_b128 v[46:49], v184 offset:30464
	ds_read_b128 v[66:69], v184 offset:30528
	s_waitcnt lgkmcnt(1)
	v_mfma_f32_16x16x32_bf16 v[46:49], v[50:53], v[46:49], 0
	s_waitcnt lgkmcnt(0)
	v_mfma_f32_16x16x32_bf16 v[46:49], v[54:57], v[66:69], v[46:49]
	ds_read_b128 v[50:53], v184 offset:30592
	ds_read_b128 v[54:57], v184 offset:30656
	s_waitcnt lgkmcnt(1)
	v_mfma_f32_16x16x32_bf16 v[46:49], v[58:61], v[50:53], v[46:49]
	s_waitcnt lgkmcnt(0)
	v_mfma_f32_16x16x32_bf16 v[46:49], v[62:65], v[54:57], v[46:49]
	s_nop 7
	s_nop 1
	v_ashrrev_i32_e32 v50, 31, v49
	v_bitop3_b32 v49, v49, v50, v217 bitop3:0x1e
	v_and_or_b32 v49, v49, s67, v178
	v_ashrrev_i32_e32 v50, 31, v45
	v_bitop3_b32 v45, v45, v50, v217 bitop3:0x1e
	v_and_or_b32 v50, v45, s67, v177
	v_ashrrev_i32_e32 v45, 31, v41
	v_bitop3_b32 v41, v41, v45, v217 bitop3:0x1e
	v_and_or_b32 v51, v41, s67, v176
	v_ashrrev_i32_e32 v41, 31, v37
	v_bitop3_b32 v37, v37, v41, v217 bitop3:0x1e
	v_and_or_b32 v52, v37, s67, v175
	v_ashrrev_i32_e32 v37, 31, v33
	v_bitop3_b32 v33, v33, v37, v217 bitop3:0x1e
	v_and_or_b32 v53, v33, s67, v170
	v_ashrrev_i32_e32 v33, 31, v29
	v_bitop3_b32 v29, v29, v33, v217 bitop3:0x1e
	v_and_or_b32 v54, v29, s67, v181
	v_ashrrev_i32_e32 v29, 31, v25
	v_bitop3_b32 v25, v25, v29, v217 bitop3:0x1e
	v_and_or_b32 v55, v25, s67, v180
	v_ashrrev_i32_e32 v25, 31, v21
	v_bitop3_b32 v21, v21, v25, v217 bitop3:0x1e
	v_and_or_b32 v21, v21, s67, v179
	v_ashrrev_i32_e32 v25, 31, v48
	v_bitop3_b32 v25, v48, v25, v217 bitop3:0x1e
	v_and_or_b32 v41, v25, s67, v178
	v_ashrrev_i32_e32 v25, 31, v44
	v_bitop3_b32 v25, v44, v25, v217 bitop3:0x1e
	v_and_or_b32 v44, v25, s67, v177
	v_ashrrev_i32_e32 v25, 31, v40
	v_bitop3_b32 v25, v40, v25, v217 bitop3:0x1e
	v_and_or_b32 v40, v25, s67, v176
	v_ashrrev_i32_e32 v25, 31, v36
	v_bitop3_b32 v25, v36, v25, v217 bitop3:0x1e
	v_and_or_b32 v45, v25, s67, v175
	v_ashrrev_i32_e32 v25, 31, v32
	v_bitop3_b32 v25, v32, v25, v217 bitop3:0x1e
	v_and_or_b32 v48, v25, s67, v170
	v_ashrrev_i32_e32 v25, 31, v28
	v_bitop3_b32 v25, v28, v25, v217 bitop3:0x1e
	v_and_or_b32 v56, v25, s67, v181
	v_ashrrev_i32_e32 v25, 31, v24
	v_bitop3_b32 v24, v24, v25, v217 bitop3:0x1e
	v_and_or_b32 v57, v24, s67, v180
	v_ashrrev_i32_e32 v24, 31, v20
	v_bitop3_b32 v20, v20, v24, v217 bitop3:0x1e
	v_and_or_b32 v20, v20, s67, v179
	v_ashrrev_i32_e32 v24, 31, v47
	v_bitop3_b32 v24, v47, v24, v217 bitop3:0x1e
	v_and_or_b32 v32, v24, s67, v178
	v_min_u32_e32 v47, v52, v51
	v_ashrrev_i32_e32 v24, 31, v43
	v_bitop3_b32 v24, v43, v24, v217 bitop3:0x1e
	v_and_or_b32 v33, v24, s67, v177
	v_ashrrev_i32_e32 v24, 31, v39
	v_bitop3_b32 v24, v39, v24, v217 bitop3:0x1e
	v_and_or_b32 v36, v24, s67, v176
	v_ashrrev_i32_e32 v24, 31, v35
	v_bitop3_b32 v24, v35, v24, v217 bitop3:0x1e
	v_and_or_b32 v35, v24, s67, v175
	v_ashrrev_i32_e32 v24, 31, v31
	v_bitop3_b32 v24, v31, v24, v217 bitop3:0x1e
	v_and_or_b32 v31, v24, s67, v170
	v_ashrrev_i32_e32 v24, 31, v27
	v_bitop3_b32 v24, v27, v24, v217 bitop3:0x1e
	v_and_or_b32 v37, v24, s67, v181
	v_ashrrev_i32_e32 v24, 31, v23
	v_bitop3_b32 v23, v23, v24, v217 bitop3:0x1e
	v_and_or_b32 v39, v23, s67, v180
	v_ashrrev_i32_e32 v23, 31, v19
	v_bitop3_b32 v19, v19, v23, v217 bitop3:0x1e
	v_and_or_b32 v19, v19, s67, v179
	v_ashrrev_i32_e32 v23, 31, v46
	v_bitop3_b32 v23, v46, v23, v217 bitop3:0x1e
	v_and_or_b32 v23, v23, s67, v178
	v_ashrrev_i32_e32 v24, 31, v42
	v_bitop3_b32 v24, v42, v24, v217 bitop3:0x1e
	v_and_or_b32 v24, v24, s67, v177
	v_ashrrev_i32_e32 v25, 31, v38
	v_bitop3_b32 v25, v38, v25, v217 bitop3:0x1e
	v_and_or_b32 v25, v25, s67, v176
	v_ashrrev_i32_e32 v27, 31, v34
	v_bitop3_b32 v27, v34, v27, v217 bitop3:0x1e
	v_and_or_b32 v27, v27, s67, v175
	v_ashrrev_i32_e32 v28, 31, v30
	v_bitop3_b32 v28, v30, v28, v217 bitop3:0x1e
	v_and_or_b32 v28, v28, s67, v170
	v_ashrrev_i32_e32 v29, 31, v26
	v_bitop3_b32 v26, v26, v29, v217 bitop3:0x1e
	v_and_or_b32 v26, v26, s67, v181
	v_ashrrev_i32_e32 v29, 31, v22
	v_bitop3_b32 v22, v22, v29, v217 bitop3:0x1e
	v_and_or_b32 v22, v22, s67, v180
	v_ashrrev_i32_e32 v29, 31, v18
	v_bitop3_b32 v18, v18, v29, v217 bitop3:0x1e
	v_and_or_b32 v18, v18, s67, v179
	v_max_u32_e32 v29, v18, v22
	v_min_u32_e32 v18, v18, v22
	v_max_u32_e32 v22, v26, v28
	v_min_u32_e32 v26, v26, v28
	v_max_u32_e32 v28, v27, v25
	v_min_u32_e32 v25, v27, v25
	v_max_u32_e32 v27, v24, v23
	v_min_u32_e32 v23, v24, v23
	v_max_u32_e32 v24, v29, v22
	v_min_u32_e32 v22, v29, v22
	v_max_u32_e32 v29, v18, v26
	v_min_u32_e32 v18, v18, v26
	v_max_u32_e32 v26, v28, v27
	v_min_u32_e32 v27, v28, v27
	v_max_u32_e32 v28, v25, v23
	v_min_u32_e32 v23, v25, v23
	v_max_u32_e32 v25, v29, v22
	v_min_u32_e32 v29, v29, v22
	v_max_u32_e32 v30, v28, v27
	v_min_u32_e32 v27, v28, v27
	v_max_u32_e32 v80, v24, v26
	v_min_u32_e32 v24, v24, v26
	v_max_u32_e32 v26, v25, v30
	v_min_u32_e32 v25, v25, v30
	v_max_u32_e32 v28, v29, v27
	v_min_u32_e32 v29, v29, v27
	v_max_u32_e32 v27, v18, v23
	v_min_u32_e32 v87, v18, v23
	v_max_u32_e32 v18, v28, v24
	v_min_u32_e32 v28, v28, v24
	v_max_u32_e32 v30, v27, v25
	v_min_u32_e32 v34, v27, v25
	v_max_u32_e32 v81, v26, v18
	v_min_u32_e32 v82, v26, v18
	v_max_u32_e32 v83, v30, v28
	v_min_u32_e32 v84, v30, v28
	v_max_u32_e32 v85, v34, v29
	v_min_u32_e32 v86, v34, v29
	v_max_u32_e32 v18, v19, v39
	v_min_u32_e32 v19, v19, v39
	v_max_u32_e32 v30, v37, v31
	v_min_u32_e32 v31, v37, v31
	v_max_u32_e32 v34, v35, v36
	v_min_u32_e32 v35, v35, v36
	v_max_u32_e32 v36, v33, v32
	v_min_u32_e32 v32, v33, v32
	v_max_u32_e32 v33, v18, v30
	v_min_u32_e32 v18, v18, v30
	v_max_u32_e32 v30, v19, v31
	v_min_u32_e32 v19, v19, v31
	v_max_u32_e32 v31, v34, v36
	v_min_u32_e32 v34, v34, v36
	v_max_u32_e32 v36, v35, v32
	v_min_u32_e32 v32, v35, v32
	v_max_u32_e32 v35, v30, v18
	v_min_u32_e32 v18, v30, v18
	v_max_u32_e32 v37, v36, v34
	v_min_u32_e32 v34, v36, v34
	v_max_u32_e32 v72, v33, v31
	v_min_u32_e32 v33, v33, v31
	v_max_u32_e32 v36, v35, v37
	v_min_u32_e32 v35, v35, v37
	v_max_u32_e32 v37, v18, v34
	v_min_u32_e32 v18, v18, v34
	v_max_u32_e32 v34, v19, v32
	v_min_u32_e32 v79, v19, v32
	v_max_u32_e32 v19, v37, v33
	v_min_u32_e32 v37, v37, v33
	v_max_u32_e32 v38, v34, v35
	v_min_u32_e32 v39, v34, v35
	v_max_u32_e32 v73, v36, v19
	v_min_u32_e32 v74, v36, v19
	v_max_u32_e32 v75, v38, v37
	v_min_u32_e32 v76, v38, v37
	v_max_u32_e32 v77, v39, v18
	v_min_u32_e32 v78, v39, v18
	v_max_u32_e32 v18, v20, v57
	v_min_u32_e32 v19, v20, v57
	v_max_u32_e32 v20, v56, v48
	v_min_u32_e32 v38, v56, v48
	v_max_u32_e32 v39, v45, v40
	v_min_u32_e32 v40, v45, v40
	v_max_u32_e32 v42, v44, v41
	v_min_u32_e32 v41, v44, v41
	v_max_u32_e32 v43, v18, v20
	v_min_u32_e32 v18, v18, v20
	v_max_u32_e32 v20, v19, v38
	v_min_u32_e32 v19, v19, v38
	v_max_u32_e32 v44, v39, v42
	v_min_u32_e32 v38, v39, v42
	v_max_u32_e32 v39, v40, v41
	v_min_u32_e32 v40, v40, v41
	v_max_u32_e32 v41, v20, v18
	v_min_u32_e32 v18, v20, v18
	v_max_u32_e32 v20, v39, v38
	v_min_u32_e32 v39, v39, v38
	v_max_u32_e32 v88, v43, v44
	v_min_u32_e32 v42, v43, v44
	v_max_u32_e32 v43, v41, v20
	v_min_u32_e32 v20, v41, v20
	v_max_u32_e32 v41, v18, v39
	v_max_u32_e32 v44, v19, v40
	v_min_u32_e32 v18, v18, v39
	v_min_u32_e32 v95, v19, v40
	v_max_u32_e32 v19, v41, v42
	v_min_u32_e32 v45, v41, v42
	v_max_u32_e32 v46, v44, v20
	v_min_u32_e32 v20, v44, v20
	v_max_u32_e32 v89, v43, v19
	v_min_u32_e32 v90, v43, v19
	v_max_u32_e32 v91, v46, v45
	v_min_u32_e32 v92, v46, v45
	v_max_u32_e32 v93, v20, v18
	v_min_u32_e32 v94, v20, v18
	v_max_u32_e32 v18, v21, v55
	v_min_u32_e32 v19, v21, v55
	v_max_u32_e32 v20, v54, v53
	v_min_u32_e32 v21, v54, v53
	v_max_u32_e32 v46, v52, v51
	v_max_u32_e32 v48, v50, v49
	v_min_u32_e32 v49, v50, v49
	v_max_u32_e32 v50, v18, v20
	v_min_u32_e32 v18, v18, v20
	v_max_u32_e32 v20, v19, v21
	v_min_u32_e32 v19, v19, v21
	v_max_u32_e32 v21, v46, v48
	v_min_u32_e32 v46, v46, v48
	v_max_u32_e32 v48, v47, v49
	v_min_u32_e32 v47, v47, v49
	v_max_u32_e32 v49, v20, v18
	v_min_u32_e32 v18, v20, v18
	v_max_u32_e32 v20, v48, v46
	v_min_u32_e32 v48, v48, v46
	v_max_u32_e32 v96, v50, v21
	v_min_u32_e32 v21, v50, v21
	v_max_u32_e32 v50, v49, v20
	v_min_u32_e32 v20, v49, v20
	v_max_u32_e32 v49, v18, v48
	v_min_u32_e32 v18, v18, v48
	v_max_u32_e32 v48, v19, v47
	v_min_u32_e32 v103, v19, v47
	v_max_u32_e32 v19, v49, v21
	v_min_u32_e32 v21, v49, v21
	v_max_u32_e32 v51, v48, v20
	v_min_u32_e32 v20, v48, v20
	v_max_u32_e32 v97, v50, v19
	v_min_u32_e32 v98, v50, v19
	v_max_u32_e32 v99, v51, v21
	v_min_u32_e32 v100, v51, v21
	v_max_u32_e32 v101, v20, v18
	v_min_u32_e32 v102, v20, v18
	v_mov_b32_e32 v18, 0
	v_mov_b32_e32 v19, 0
	v_mov_b32_e32 v20, 0
	v_mov_b32_e32 v21, 0
.LBB0_1347:
	v_max_u32_dpp v55, v72, v72 row_ror:1 row_mask:0xf bank_mask:0xf bound_ctrl:1
	v_max_u32_dpp v54, v80, v80 row_ror:1 row_mask:0xf bank_mask:0xf bound_ctrl:1
	v_max_u32_dpp v56, v88, v88 row_ror:1 row_mask:0xf bank_mask:0xf bound_ctrl:1
	v_max_u32_dpp v55, v55, v55 row_ror:2 row_mask:0xf bank_mask:0xf bound_ctrl:1
	v_max_u32_dpp v57, v96, v96 row_ror:1 row_mask:0xf bank_mask:0xf bound_ctrl:1
	v_max_u32_dpp v54, v54, v54 row_ror:2 row_mask:0xf bank_mask:0xf bound_ctrl:1
	v_max_u32_dpp v56, v56, v56 row_ror:2 row_mask:0xf bank_mask:0xf bound_ctrl:1
	v_max_u32_dpp v55, v55, v55 row_ror:4 row_mask:0xf bank_mask:0xf bound_ctrl:1
	v_max_u32_dpp v57, v57, v57 row_ror:2 row_mask:0xf bank_mask:0xf bound_ctrl:1
	v_max_u32_dpp v54, v54, v54 row_ror:4 row_mask:0xf bank_mask:0xf bound_ctrl:1
	v_max_u32_dpp v56, v56, v56 row_ror:4 row_mask:0xf bank_mask:0xf bound_ctrl:1
	v_max_u32_dpp v55, v55, v55 row_ror:8 row_mask:0xf bank_mask:0xf bound_ctrl:1
	v_max_u32_dpp v57, v57, v57 row_ror:4 row_mask:0xf bank_mask:0xf bound_ctrl:1
	v_max_u32_dpp v54, v54, v54 row_ror:8 row_mask:0xf bank_mask:0xf bound_ctrl:1
	v_max_u32_dpp v56, v56, v56 row_ror:8 row_mask:0xf bank_mask:0xf bound_ctrl:1
	v_max_u32_dpp v57, v57, v57 row_ror:8 row_mask:0xf bank_mask:0xf bound_ctrl:1
	v_cmp_eq_u32_e64 s[84:85], v72, v55
	v_cmp_eq_u32_e64 s[86:87], v80, v54
	v_cmp_eq_u32_e64 s[88:89], v88, v56
	v_cmp_eq_u32_e64 s[90:91], v96, v57
	s_mov_b64 exec, s[84:85]
	v_pk_mov_b32 v[72:73], v[72:73], v[74:75] op_sel:[1,0] op_sel_hi:[1,0]
	v_pk_mov_b32 v[74:75], v[74:75], v[76:77] op_sel:[1,0] op_sel_hi:[1,0]
	v_pk_mov_b32 v[76:77], v[76:77], v[78:79] op_sel:[1,0] op_sel_hi:[1,0]
	v_pk_mov_b32 v[78:79], v[78:79], v[70:71] op_sel:[1,0] op_sel_hi:[1,0]
	s_mov_b64 exec, s[86:87]
	v_pk_mov_b32 v[80:81], v[80:81], v[82:83] op_sel:[1,0] op_sel_hi:[1,0]
	v_pk_mov_b32 v[82:83], v[82:83], v[84:85] op_sel:[1,0] op_sel_hi:[1,0]
	v_pk_mov_b32 v[84:85], v[84:85], v[86:87] op_sel:[1,0] op_sel_hi:[1,0]
	v_pk_mov_b32 v[86:87], v[86:87], v[70:71] op_sel:[1,0] op_sel_hi:[1,0]
	s_mov_b64 exec, s[88:89]
	v_pk_mov_b32 v[88:89], v[88:89], v[90:91] op_sel:[1,0] op_sel_hi:[1,0]
	v_pk_mov_b32 v[90:91], v[90:91], v[92:93] op_sel:[1,0] op_sel_hi:[1,0]
	v_pk_mov_b32 v[92:93], v[92:93], v[94:95] op_sel:[1,0] op_sel_hi:[1,0]
	v_pk_mov_b32 v[94:95], v[94:95], v[70:71] op_sel:[1,0] op_sel_hi:[1,0]
	s_mov_b64 exec, s[90:91]
	v_pk_mov_b32 v[96:97], v[96:97], v[98:99] op_sel:[1,0] op_sel_hi:[1,0]
	v_pk_mov_b32 v[98:99], v[98:99], v[100:101] op_sel:[1,0] op_sel_hi:[1,0]
	v_pk_mov_b32 v[100:101], v[100:101], v[102:103] op_sel:[1,0] op_sel_hi:[1,0]
	v_pk_mov_b32 v[102:103], v[102:103], v[70:71] op_sel:[1,0] op_sel_hi:[1,0]
	s_lshl_b64 exec, s[78:79], s40
	s_add_i32 s40, s40, 1
	v_pk_mov_b32 v[18:19], v[54:55], v[54:55] op_sel:[0,1] op_sel_hi:[0,1]
	v_pk_mov_b32 v[20:21], v[56:57], v[56:57] op_sel:[0,1] op_sel_hi:[0,1]
	s_mov_b64 exec, -1
	s_cmp_lg_u32 s40, 8
	s_cbranch_scc1 .LBB0_1347
	v_max_u32_dpp v55, v72, v72 row_ror:1 row_mask:0xf bank_mask:0xf bound_ctrl:1
	v_max_u32_dpp v54, v80, v80 row_ror:1 row_mask:0xf bank_mask:0xf bound_ctrl:1
	v_max_u32_dpp v56, v88, v88 row_ror:1 row_mask:0xf bank_mask:0xf bound_ctrl:1
	v_max_u32_dpp v55, v55, v55 row_ror:2 row_mask:0xf bank_mask:0xf bound_ctrl:1
	v_max_u32_dpp v57, v96, v96 row_ror:1 row_mask:0xf bank_mask:0xf bound_ctrl:1
	v_max_u32_dpp v54, v54, v54 row_ror:2 row_mask:0xf bank_mask:0xf bound_ctrl:1
	v_max_u32_dpp v56, v56, v56 row_ror:2 row_mask:0xf bank_mask:0xf bound_ctrl:1
	v_max_u32_dpp v55, v55, v55 row_ror:4 row_mask:0xf bank_mask:0xf bound_ctrl:1
	v_max_u32_dpp v57, v57, v57 row_ror:2 row_mask:0xf bank_mask:0xf bound_ctrl:1
	v_max_u32_dpp v54, v54, v54 row_ror:4 row_mask:0xf bank_mask:0xf bound_ctrl:1
	v_max_u32_dpp v56, v56, v56 row_ror:4 row_mask:0xf bank_mask:0xf bound_ctrl:1
	v_max_u32_dpp v55, v55, v55 row_ror:8 row_mask:0xf bank_mask:0xf bound_ctrl:1
	v_max_u32_dpp v57, v57, v57 row_ror:4 row_mask:0xf bank_mask:0xf bound_ctrl:1
	v_max_u32_dpp v54, v54, v54 row_ror:8 row_mask:0xf bank_mask:0xf bound_ctrl:1
	v_max_u32_dpp v56, v56, v56 row_ror:8 row_mask:0xf bank_mask:0xf bound_ctrl:1
	v_max_u32_dpp v57, v57, v57 row_ror:8 row_mask:0xf bank_mask:0xf bound_ctrl:1
	v_cmp_eq_u32_e64 s[84:85], v72, v55
	v_cmp_eq_u32_e64 s[86:87], v80, v54
	v_cmp_eq_u32_e64 s[88:89], v88, v56
	v_cmp_eq_u32_e64 s[90:91], v96, v57
	s_mov_b64 exec, s[84:85]
	v_pk_mov_b32 v[72:73], v[72:73], v[74:75] op_sel:[1,0] op_sel_hi:[1,0]
	v_pk_mov_b32 v[74:75], v[74:75], v[76:77] op_sel:[1,0] op_sel_hi:[1,0]
	v_pk_mov_b32 v[76:77], v[76:77], v[78:79] op_sel:[1,0] op_sel_hi:[1,0]
	v_pk_mov_b32 v[78:79], v[78:79], v[70:71] op_sel:[1,0] op_sel_hi:[1,0]
	s_mov_b64 exec, s[86:87]
	v_pk_mov_b32 v[80:81], v[80:81], v[82:83] op_sel:[1,0] op_sel_hi:[1,0]
	v_pk_mov_b32 v[82:83], v[82:83], v[84:85] op_sel:[1,0] op_sel_hi:[1,0]
	v_pk_mov_b32 v[84:85], v[84:85], v[86:87] op_sel:[1,0] op_sel_hi:[1,0]
	v_pk_mov_b32 v[86:87], v[86:87], v[70:71] op_sel:[1,0] op_sel_hi:[1,0]
	s_mov_b64 exec, s[88:89]
	v_pk_mov_b32 v[88:89], v[88:89], v[90:91] op_sel:[1,0] op_sel_hi:[1,0]
	v_pk_mov_b32 v[90:91], v[90:91], v[92:93] op_sel:[1,0] op_sel_hi:[1,0]
	v_pk_mov_b32 v[92:93], v[92:93], v[94:95] op_sel:[1,0] op_sel_hi:[1,0]
	v_pk_mov_b32 v[94:95], v[94:95], v[70:71] op_sel:[1,0] op_sel_hi:[1,0]
	s_mov_b64 exec, s[90:91]
	v_pk_mov_b32 v[96:97], v[96:97], v[98:99] op_sel:[1,0] op_sel_hi:[1,0]
	v_pk_mov_b32 v[98:99], v[98:99], v[100:101] op_sel:[1,0] op_sel_hi:[1,0]
	v_pk_mov_b32 v[100:101], v[100:101], v[102:103] op_sel:[1,0] op_sel_hi:[1,0]
	v_pk_mov_b32 v[102:103], v[102:103], v[70:71] op_sel:[1,0] op_sel_hi:[1,0]
	s_lshl_b64 exec, s[78:79], s40
	s_add_i32 s40, s40, 1
	v_pk_mov_b32 v[18:19], v[54:55], v[54:55] op_sel:[0,1] op_sel_hi:[0,1]
	v_pk_mov_b32 v[20:21], v[56:57], v[56:57] op_sel:[0,1] op_sel_hi:[0,1]
	s_mov_b64 exec, -1
	v_max_u32_dpp v55, v72, v72 row_ror:1 row_mask:0xf bank_mask:0xf bound_ctrl:1
	v_max_u32_dpp v54, v80, v80 row_ror:1 row_mask:0xf bank_mask:0xf bound_ctrl:1
	v_max_u32_dpp v56, v88, v88 row_ror:1 row_mask:0xf bank_mask:0xf bound_ctrl:1
	v_max_u32_dpp v55, v55, v55 row_ror:2 row_mask:0xf bank_mask:0xf bound_ctrl:1
	v_max_u32_dpp v57, v96, v96 row_ror:1 row_mask:0xf bank_mask:0xf bound_ctrl:1
	v_max_u32_dpp v54, v54, v54 row_ror:2 row_mask:0xf bank_mask:0xf bound_ctrl:1
	v_max_u32_dpp v56, v56, v56 row_ror:2 row_mask:0xf bank_mask:0xf bound_ctrl:1
	v_max_u32_dpp v55, v55, v55 row_ror:4 row_mask:0xf bank_mask:0xf bound_ctrl:1
	v_max_u32_dpp v57, v57, v57 row_ror:2 row_mask:0xf bank_mask:0xf bound_ctrl:1
	v_max_u32_dpp v54, v54, v54 row_ror:4 row_mask:0xf bank_mask:0xf bound_ctrl:1
	v_max_u32_dpp v56, v56, v56 row_ror:4 row_mask:0xf bank_mask:0xf bound_ctrl:1
	v_max_u32_dpp v55, v55, v55 row_ror:8 row_mask:0xf bank_mask:0xf bound_ctrl:1
	v_max_u32_dpp v57, v57, v57 row_ror:4 row_mask:0xf bank_mask:0xf bound_ctrl:1
	v_max_u32_dpp v54, v54, v54 row_ror:8 row_mask:0xf bank_mask:0xf bound_ctrl:1
	v_max_u32_dpp v56, v56, v56 row_ror:8 row_mask:0xf bank_mask:0xf bound_ctrl:1
	v_max_u32_dpp v57, v57, v57 row_ror:8 row_mask:0xf bank_mask:0xf bound_ctrl:1
	v_cmp_eq_u32_e64 s[84:85], v72, v55
	v_cmp_eq_u32_e64 s[86:87], v80, v54
	v_cmp_eq_u32_e64 s[88:89], v88, v56
	v_cmp_eq_u32_e64 s[90:91], v96, v57
	s_mov_b64 exec, s[84:85]
	v_pk_mov_b32 v[72:73], v[72:73], v[74:75] op_sel:[1,0] op_sel_hi:[1,0]
	v_pk_mov_b32 v[74:75], v[74:75], v[76:77] op_sel:[1,0] op_sel_hi:[1,0]
	v_pk_mov_b32 v[76:77], v[76:77], v[78:79] op_sel:[1,0] op_sel_hi:[1,0]
	s_mov_b64 exec, s[86:87]
	v_pk_mov_b32 v[80:81], v[80:81], v[82:83] op_sel:[1,0] op_sel_hi:[1,0]
	v_pk_mov_b32 v[82:83], v[82:83], v[84:85] op_sel:[1,0] op_sel_hi:[1,0]
	v_pk_mov_b32 v[84:85], v[84:85], v[86:87] op_sel:[1,0] op_sel_hi:[1,0]
	s_mov_b64 exec, s[88:89]
	v_pk_mov_b32 v[88:89], v[88:89], v[90:91] op_sel:[1,0] op_sel_hi:[1,0]
	v_pk_mov_b32 v[90:91], v[90:91], v[92:93] op_sel:[1,0] op_sel_hi:[1,0]
	v_pk_mov_b32 v[92:93], v[92:93], v[94:95] op_sel:[1,0] op_sel_hi:[1,0]
	s_mov_b64 exec, s[90:91]
	v_pk_mov_b32 v[96:97], v[96:97], v[98:99] op_sel:[1,0] op_sel_hi:[1,0]
	v_pk_mov_b32 v[98:99], v[98:99], v[100:101] op_sel:[1,0] op_sel_hi:[1,0]
	v_pk_mov_b32 v[100:101], v[100:101], v[102:103] op_sel:[1,0] op_sel_hi:[1,0]
	s_lshl_b64 exec, s[78:79], s40
	s_add_i32 s40, s40, 1
	v_pk_mov_b32 v[18:19], v[54:55], v[54:55] op_sel:[0,1] op_sel_hi:[0,1]
	v_pk_mov_b32 v[20:21], v[56:57], v[56:57] op_sel:[0,1] op_sel_hi:[0,1]
	s_mov_b64 exec, -1
	v_max_u32_dpp v55, v72, v72 row_ror:1 row_mask:0xf bank_mask:0xf bound_ctrl:1
	v_max_u32_dpp v54, v80, v80 row_ror:1 row_mask:0xf bank_mask:0xf bound_ctrl:1
	v_max_u32_dpp v56, v88, v88 row_ror:1 row_mask:0xf bank_mask:0xf bound_ctrl:1
	v_max_u32_dpp v55, v55, v55 row_ror:2 row_mask:0xf bank_mask:0xf bound_ctrl:1
	v_max_u32_dpp v57, v96, v96 row_ror:1 row_mask:0xf bank_mask:0xf bound_ctrl:1
	v_max_u32_dpp v54, v54, v54 row_ror:2 row_mask:0xf bank_mask:0xf bound_ctrl:1
	v_max_u32_dpp v56, v56, v56 row_ror:2 row_mask:0xf bank_mask:0xf bound_ctrl:1
	v_max_u32_dpp v55, v55, v55 row_ror:4 row_mask:0xf bank_mask:0xf bound_ctrl:1
	v_max_u32_dpp v57, v57, v57 row_ror:2 row_mask:0xf bank_mask:0xf bound_ctrl:1
	v_max_u32_dpp v54, v54, v54 row_ror:4 row_mask:0xf bank_mask:0xf bound_ctrl:1
	v_max_u32_dpp v56, v56, v56 row_ror:4 row_mask:0xf bank_mask:0xf bound_ctrl:1
	v_max_u32_dpp v55, v55, v55 row_ror:8 row_mask:0xf bank_mask:0xf bound_ctrl:1
	v_max_u32_dpp v57, v57, v57 row_ror:4 row_mask:0xf bank_mask:0xf bound_ctrl:1
	v_max_u32_dpp v54, v54, v54 row_ror:8 row_mask:0xf bank_mask:0xf bound_ctrl:1
	v_max_u32_dpp v56, v56, v56 row_ror:8 row_mask:0xf bank_mask:0xf bound_ctrl:1
	v_max_u32_dpp v57, v57, v57 row_ror:8 row_mask:0xf bank_mask:0xf bound_ctrl:1
	v_cmp_eq_u32_e64 s[84:85], v72, v55
	v_cmp_eq_u32_e64 s[86:87], v80, v54
	v_cmp_eq_u32_e64 s[88:89], v88, v56
	v_cmp_eq_u32_e64 s[90:91], v96, v57
	s_mov_b64 exec, s[84:85]
	v_pk_mov_b32 v[72:73], v[72:73], v[74:75] op_sel:[1,0] op_sel_hi:[1,0]
	v_pk_mov_b32 v[74:75], v[74:75], v[76:77] op_sel:[1,0] op_sel_hi:[1,0]
	v_pk_mov_b32 v[76:77], v[76:77], v[78:79] op_sel:[1,0] op_sel_hi:[1,0]
	s_mov_b64 exec, s[86:87]
	v_pk_mov_b32 v[80:81], v[80:81], v[82:83] op_sel:[1,0] op_sel_hi:[1,0]
	v_pk_mov_b32 v[82:83], v[82:83], v[84:85] op_sel:[1,0] op_sel_hi:[1,0]
	v_pk_mov_b32 v[84:85], v[84:85], v[86:87] op_sel:[1,0] op_sel_hi:[1,0]
	s_mov_b64 exec, s[88:89]
	v_pk_mov_b32 v[88:89], v[88:89], v[90:91] op_sel:[1,0] op_sel_hi:[1,0]
	v_pk_mov_b32 v[90:91], v[90:91], v[92:93] op_sel:[1,0] op_sel_hi:[1,0]
	v_pk_mov_b32 v[92:93], v[92:93], v[94:95] op_sel:[1,0] op_sel_hi:[1,0]
	s_mov_b64 exec, s[90:91]
	v_pk_mov_b32 v[96:97], v[96:97], v[98:99] op_sel:[1,0] op_sel_hi:[1,0]
	v_pk_mov_b32 v[98:99], v[98:99], v[100:101] op_sel:[1,0] op_sel_hi:[1,0]
	v_pk_mov_b32 v[100:101], v[100:101], v[102:103] op_sel:[1,0] op_sel_hi:[1,0]
	s_lshl_b64 exec, s[78:79], s40
	s_add_i32 s40, s40, 1
	v_pk_mov_b32 v[18:19], v[54:55], v[54:55] op_sel:[0,1] op_sel_hi:[0,1]
	v_pk_mov_b32 v[20:21], v[56:57], v[56:57] op_sel:[0,1] op_sel_hi:[0,1]
	s_mov_b64 exec, -1
	v_max_u32_dpp v55, v72, v72 row_ror:1 row_mask:0xf bank_mask:0xf bound_ctrl:1
	v_max_u32_dpp v54, v80, v80 row_ror:1 row_mask:0xf bank_mask:0xf bound_ctrl:1
	v_max_u32_dpp v56, v88, v88 row_ror:1 row_mask:0xf bank_mask:0xf bound_ctrl:1
	v_max_u32_dpp v55, v55, v55 row_ror:2 row_mask:0xf bank_mask:0xf bound_ctrl:1
	v_max_u32_dpp v57, v96, v96 row_ror:1 row_mask:0xf bank_mask:0xf bound_ctrl:1
	v_max_u32_dpp v54, v54, v54 row_ror:2 row_mask:0xf bank_mask:0xf bound_ctrl:1
	v_max_u32_dpp v56, v56, v56 row_ror:2 row_mask:0xf bank_mask:0xf bound_ctrl:1
	v_max_u32_dpp v55, v55, v55 row_ror:4 row_mask:0xf bank_mask:0xf bound_ctrl:1
	v_max_u32_dpp v57, v57, v57 row_ror:2 row_mask:0xf bank_mask:0xf bound_ctrl:1
	v_max_u32_dpp v54, v54, v54 row_ror:4 row_mask:0xf bank_mask:0xf bound_ctrl:1
	v_max_u32_dpp v56, v56, v56 row_ror:4 row_mask:0xf bank_mask:0xf bound_ctrl:1
	v_max_u32_dpp v55, v55, v55 row_ror:8 row_mask:0xf bank_mask:0xf bound_ctrl:1
	v_max_u32_dpp v57, v57, v57 row_ror:4 row_mask:0xf bank_mask:0xf bound_ctrl:1
	v_max_u32_dpp v54, v54, v54 row_ror:8 row_mask:0xf bank_mask:0xf bound_ctrl:1
	v_max_u32_dpp v56, v56, v56 row_ror:8 row_mask:0xf bank_mask:0xf bound_ctrl:1
	v_max_u32_dpp v57, v57, v57 row_ror:8 row_mask:0xf bank_mask:0xf bound_ctrl:1
	v_cmp_eq_u32_e64 s[84:85], v72, v55
	v_cmp_eq_u32_e64 s[86:87], v80, v54
	v_cmp_eq_u32_e64 s[88:89], v88, v56
	v_cmp_eq_u32_e64 s[90:91], v96, v57
	s_mov_b64 exec, s[84:85]
	v_pk_mov_b32 v[72:73], v[72:73], v[74:75] op_sel:[1,0] op_sel_hi:[1,0]
	v_pk_mov_b32 v[74:75], v[74:75], v[76:77] op_sel:[1,0] op_sel_hi:[1,0]
	s_mov_b64 exec, s[86:87]
	v_pk_mov_b32 v[80:81], v[80:81], v[82:83] op_sel:[1,0] op_sel_hi:[1,0]
	v_pk_mov_b32 v[82:83], v[82:83], v[84:85] op_sel:[1,0] op_sel_hi:[1,0]
	s_mov_b64 exec, s[88:89]
	v_pk_mov_b32 v[88:89], v[88:89], v[90:91] op_sel:[1,0] op_sel_hi:[1,0]
	v_pk_mov_b32 v[90:91], v[90:91], v[92:93] op_sel:[1,0] op_sel_hi:[1,0]
	s_mov_b64 exec, s[90:91]
	v_pk_mov_b32 v[96:97], v[96:97], v[98:99] op_sel:[1,0] op_sel_hi:[1,0]
	v_pk_mov_b32 v[98:99], v[98:99], v[100:101] op_sel:[1,0] op_sel_hi:[1,0]
	s_lshl_b64 exec, s[78:79], s40
	s_add_i32 s40, s40, 1
	v_pk_mov_b32 v[18:19], v[54:55], v[54:55] op_sel:[0,1] op_sel_hi:[0,1]
	v_pk_mov_b32 v[20:21], v[56:57], v[56:57] op_sel:[0,1] op_sel_hi:[0,1]
	s_mov_b64 exec, -1
	v_max_u32_dpp v55, v72, v72 row_ror:1 row_mask:0xf bank_mask:0xf bound_ctrl:1
	v_max_u32_dpp v54, v80, v80 row_ror:1 row_mask:0xf bank_mask:0xf bound_ctrl:1
	v_max_u32_dpp v56, v88, v88 row_ror:1 row_mask:0xf bank_mask:0xf bound_ctrl:1
	v_max_u32_dpp v55, v55, v55 row_ror:2 row_mask:0xf bank_mask:0xf bound_ctrl:1
	v_max_u32_dpp v57, v96, v96 row_ror:1 row_mask:0xf bank_mask:0xf bound_ctrl:1
	v_max_u32_dpp v54, v54, v54 row_ror:2 row_mask:0xf bank_mask:0xf bound_ctrl:1
	v_max_u32_dpp v56, v56, v56 row_ror:2 row_mask:0xf bank_mask:0xf bound_ctrl:1
	v_max_u32_dpp v55, v55, v55 row_ror:4 row_mask:0xf bank_mask:0xf bound_ctrl:1
	v_max_u32_dpp v57, v57, v57 row_ror:2 row_mask:0xf bank_mask:0xf bound_ctrl:1
	v_max_u32_dpp v54, v54, v54 row_ror:4 row_mask:0xf bank_mask:0xf bound_ctrl:1
	v_max_u32_dpp v56, v56, v56 row_ror:4 row_mask:0xf bank_mask:0xf bound_ctrl:1
	v_max_u32_dpp v55, v55, v55 row_ror:8 row_mask:0xf bank_mask:0xf bound_ctrl:1
	v_max_u32_dpp v57, v57, v57 row_ror:4 row_mask:0xf bank_mask:0xf bound_ctrl:1
	v_max_u32_dpp v54, v54, v54 row_ror:8 row_mask:0xf bank_mask:0xf bound_ctrl:1
	v_max_u32_dpp v56, v56, v56 row_ror:8 row_mask:0xf bank_mask:0xf bound_ctrl:1
	v_max_u32_dpp v57, v57, v57 row_ror:8 row_mask:0xf bank_mask:0xf bound_ctrl:1
	v_cmp_eq_u32_e64 s[84:85], v72, v55
	v_cmp_eq_u32_e64 s[86:87], v80, v54
	v_cmp_eq_u32_e64 s[88:89], v88, v56
	v_cmp_eq_u32_e64 s[90:91], v96, v57
	s_mov_b64 exec, s[84:85]
	v_pk_mov_b32 v[72:73], v[72:73], v[74:75] op_sel:[1,0] op_sel_hi:[1,0]
	v_pk_mov_b32 v[74:75], v[74:75], v[76:77] op_sel:[1,0] op_sel_hi:[1,0]
	s_mov_b64 exec, s[86:87]
	v_pk_mov_b32 v[80:81], v[80:81], v[82:83] op_sel:[1,0] op_sel_hi:[1,0]
	v_pk_mov_b32 v[82:83], v[82:83], v[84:85] op_sel:[1,0] op_sel_hi:[1,0]
	s_mov_b64 exec, s[88:89]
	v_pk_mov_b32 v[88:89], v[88:89], v[90:91] op_sel:[1,0] op_sel_hi:[1,0]
	v_pk_mov_b32 v[90:91], v[90:91], v[92:93] op_sel:[1,0] op_sel_hi:[1,0]
	s_mov_b64 exec, s[90:91]
	v_pk_mov_b32 v[96:97], v[96:97], v[98:99] op_sel:[1,0] op_sel_hi:[1,0]
	v_pk_mov_b32 v[98:99], v[98:99], v[100:101] op_sel:[1,0] op_sel_hi:[1,0]
	s_lshl_b64 exec, s[78:79], s40
	s_add_i32 s40, s40, 1
	v_pk_mov_b32 v[18:19], v[54:55], v[54:55] op_sel:[0,1] op_sel_hi:[0,1]
	v_pk_mov_b32 v[20:21], v[56:57], v[56:57] op_sel:[0,1] op_sel_hi:[0,1]
	s_mov_b64 exec, -1
	v_max_u32_dpp v55, v72, v72 row_ror:1 row_mask:0xf bank_mask:0xf bound_ctrl:1
	v_max_u32_dpp v54, v80, v80 row_ror:1 row_mask:0xf bank_mask:0xf bound_ctrl:1
	v_max_u32_dpp v56, v88, v88 row_ror:1 row_mask:0xf bank_mask:0xf bound_ctrl:1
	v_max_u32_dpp v55, v55, v55 row_ror:2 row_mask:0xf bank_mask:0xf bound_ctrl:1
	v_max_u32_dpp v57, v96, v96 row_ror:1 row_mask:0xf bank_mask:0xf bound_ctrl:1
	v_max_u32_dpp v54, v54, v54 row_ror:2 row_mask:0xf bank_mask:0xf bound_ctrl:1
	v_max_u32_dpp v56, v56, v56 row_ror:2 row_mask:0xf bank_mask:0xf bound_ctrl:1
	v_max_u32_dpp v55, v55, v55 row_ror:4 row_mask:0xf bank_mask:0xf bound_ctrl:1
	v_max_u32_dpp v57, v57, v57 row_ror:2 row_mask:0xf bank_mask:0xf bound_ctrl:1
	v_max_u32_dpp v54, v54, v54 row_ror:4 row_mask:0xf bank_mask:0xf bound_ctrl:1
	v_max_u32_dpp v56, v56, v56 row_ror:4 row_mask:0xf bank_mask:0xf bound_ctrl:1
	v_max_u32_dpp v55, v55, v55 row_ror:8 row_mask:0xf bank_mask:0xf bound_ctrl:1
	v_max_u32_dpp v57, v57, v57 row_ror:4 row_mask:0xf bank_mask:0xf bound_ctrl:1
	v_max_u32_dpp v54, v54, v54 row_ror:8 row_mask:0xf bank_mask:0xf bound_ctrl:1
	v_max_u32_dpp v56, v56, v56 row_ror:8 row_mask:0xf bank_mask:0xf bound_ctrl:1
	v_max_u32_dpp v57, v57, v57 row_ror:8 row_mask:0xf bank_mask:0xf bound_ctrl:1
	v_cmp_eq_u32_e64 s[84:85], v72, v55
	v_cmp_eq_u32_e64 s[86:87], v80, v54
	v_cmp_eq_u32_e64 s[88:89], v88, v56
	v_cmp_eq_u32_e64 s[90:91], v96, v57
	s_mov_b64 exec, s[84:85]
	v_pk_mov_b32 v[72:73], v[72:73], v[74:75] op_sel:[1,0] op_sel_hi:[1,0]
	s_mov_b64 exec, s[86:87]
	v_pk_mov_b32 v[80:81], v[80:81], v[82:83] op_sel:[1,0] op_sel_hi:[1,0]
	s_mov_b64 exec, s[88:89]
	v_pk_mov_b32 v[88:89], v[88:89], v[90:91] op_sel:[1,0] op_sel_hi:[1,0]
	s_mov_b64 exec, s[90:91]
	v_pk_mov_b32 v[96:97], v[96:97], v[98:99] op_sel:[1,0] op_sel_hi:[1,0]
	s_lshl_b64 exec, s[78:79], s40
	s_add_i32 s40, s40, 1
	v_pk_mov_b32 v[18:19], v[54:55], v[54:55] op_sel:[0,1] op_sel_hi:[0,1]
	v_pk_mov_b32 v[20:21], v[56:57], v[56:57] op_sel:[0,1] op_sel_hi:[0,1]
	s_mov_b64 exec, -1
	v_max_u32_dpp v55, v72, v72 row_ror:1 row_mask:0xf bank_mask:0xf bound_ctrl:1
	v_max_u32_dpp v54, v80, v80 row_ror:1 row_mask:0xf bank_mask:0xf bound_ctrl:1
	v_max_u32_dpp v56, v88, v88 row_ror:1 row_mask:0xf bank_mask:0xf bound_ctrl:1
	v_max_u32_dpp v55, v55, v55 row_ror:2 row_mask:0xf bank_mask:0xf bound_ctrl:1
	v_max_u32_dpp v57, v96, v96 row_ror:1 row_mask:0xf bank_mask:0xf bound_ctrl:1
	v_max_u32_dpp v54, v54, v54 row_ror:2 row_mask:0xf bank_mask:0xf bound_ctrl:1
	v_max_u32_dpp v56, v56, v56 row_ror:2 row_mask:0xf bank_mask:0xf bound_ctrl:1
	v_max_u32_dpp v55, v55, v55 row_ror:4 row_mask:0xf bank_mask:0xf bound_ctrl:1
	v_max_u32_dpp v57, v57, v57 row_ror:2 row_mask:0xf bank_mask:0xf bound_ctrl:1
	v_max_u32_dpp v54, v54, v54 row_ror:4 row_mask:0xf bank_mask:0xf bound_ctrl:1
	v_max_u32_dpp v56, v56, v56 row_ror:4 row_mask:0xf bank_mask:0xf bound_ctrl:1
	v_max_u32_dpp v55, v55, v55 row_ror:8 row_mask:0xf bank_mask:0xf bound_ctrl:1
	v_max_u32_dpp v57, v57, v57 row_ror:4 row_mask:0xf bank_mask:0xf bound_ctrl:1
	v_max_u32_dpp v54, v54, v54 row_ror:8 row_mask:0xf bank_mask:0xf bound_ctrl:1
	v_max_u32_dpp v56, v56, v56 row_ror:8 row_mask:0xf bank_mask:0xf bound_ctrl:1
	v_max_u32_dpp v57, v57, v57 row_ror:8 row_mask:0xf bank_mask:0xf bound_ctrl:1
	v_cmp_eq_u32_e64 s[84:85], v72, v55
	v_cmp_eq_u32_e64 s[86:87], v80, v54
	v_cmp_eq_u32_e64 s[88:89], v88, v56
	v_cmp_eq_u32_e64 s[90:91], v96, v57
	s_mov_b64 exec, s[84:85]
	v_pk_mov_b32 v[72:73], v[72:73], v[74:75] op_sel:[1,0] op_sel_hi:[1,0]
	s_mov_b64 exec, s[86:87]
	v_pk_mov_b32 v[80:81], v[80:81], v[82:83] op_sel:[1,0] op_sel_hi:[1,0]
	s_mov_b64 exec, s[88:89]
	v_pk_mov_b32 v[88:89], v[88:89], v[90:91] op_sel:[1,0] op_sel_hi:[1,0]
	s_mov_b64 exec, s[90:91]
	v_pk_mov_b32 v[96:97], v[96:97], v[98:99] op_sel:[1,0] op_sel_hi:[1,0]
	s_lshl_b64 exec, s[78:79], s40
	s_add_i32 s40, s40, 1
	v_pk_mov_b32 v[18:19], v[54:55], v[54:55] op_sel:[0,1] op_sel_hi:[0,1]
	v_pk_mov_b32 v[20:21], v[56:57], v[56:57] op_sel:[0,1] op_sel_hi:[0,1]
	s_mov_b64 exec, -1
	v_max_u32_dpp v55, v72, v72 row_ror:1 row_mask:0xf bank_mask:0xf bound_ctrl:1
	v_max_u32_dpp v54, v80, v80 row_ror:1 row_mask:0xf bank_mask:0xf bound_ctrl:1
	v_max_u32_dpp v56, v88, v88 row_ror:1 row_mask:0xf bank_mask:0xf bound_ctrl:1
	v_max_u32_dpp v55, v55, v55 row_ror:2 row_mask:0xf bank_mask:0xf bound_ctrl:1
	v_max_u32_dpp v57, v96, v96 row_ror:1 row_mask:0xf bank_mask:0xf bound_ctrl:1
	v_max_u32_dpp v54, v54, v54 row_ror:2 row_mask:0xf bank_mask:0xf bound_ctrl:1
	v_max_u32_dpp v56, v56, v56 row_ror:2 row_mask:0xf bank_mask:0xf bound_ctrl:1
	v_max_u32_dpp v55, v55, v55 row_ror:4 row_mask:0xf bank_mask:0xf bound_ctrl:1
	v_max_u32_dpp v57, v57, v57 row_ror:2 row_mask:0xf bank_mask:0xf bound_ctrl:1
	v_max_u32_dpp v54, v54, v54 row_ror:4 row_mask:0xf bank_mask:0xf bound_ctrl:1
	v_max_u32_dpp v56, v56, v56 row_ror:4 row_mask:0xf bank_mask:0xf bound_ctrl:1
	v_max_u32_dpp v55, v55, v55 row_ror:8 row_mask:0xf bank_mask:0xf bound_ctrl:1
	v_max_u32_dpp v57, v57, v57 row_ror:4 row_mask:0xf bank_mask:0xf bound_ctrl:1
	v_max_u32_dpp v54, v54, v54 row_ror:8 row_mask:0xf bank_mask:0xf bound_ctrl:1
	v_max_u32_dpp v56, v56, v56 row_ror:8 row_mask:0xf bank_mask:0xf bound_ctrl:1
	v_max_u32_dpp v57, v57, v57 row_ror:8 row_mask:0xf bank_mask:0xf bound_ctrl:1
	s_lshl_b64 exec, s[78:79], s40
	v_pk_mov_b32 v[18:19], v[54:55], v[54:55] op_sel:[0,1] op_sel_hi:[0,1]
	v_pk_mov_b32 v[20:21], v[56:57], v[56:57] op_sel:[0,1] op_sel_hi:[0,1]
	s_mov_b64 exec, -1
	ds_read_b128 v[22:25], v184 offset:34816
	ds_read_b128 v[26:29], v184 offset:34880
	s_waitcnt lgkmcnt(1)
	v_mfma_f32_16x16x32_bf16 v[22:25], v[12:15], v[22:25], 0
	s_waitcnt lgkmcnt(0)
	v_mfma_f32_16x16x32_bf16 v[22:25], v[8:11], v[26:29], v[22:25]
	ds_read_b128 v[26:29], v184 offset:34944
	s_waitcnt lgkmcnt(0)
	v_mfma_f32_16x16x32_bf16 v[22:25], v[4:7], v[26:29], v[22:25]
	ds_read_b128 v[26:29], v184 offset:35008
	s_waitcnt lgkmcnt(0)
	v_mfma_f32_16x16x32_bf16 v[22:25], v[0:3], v[26:29], v[22:25]
	ds_read_b128 v[26:29], v184 offset:39168
	ds_read_b128 v[30:33], v184 offset:39232
	s_waitcnt lgkmcnt(1)
	v_mfma_f32_16x16x32_bf16 v[26:29], v[12:15], v[26:29], 0
	s_waitcnt lgkmcnt(0)
	v_mfma_f32_16x16x32_bf16 v[26:29], v[8:11], v[30:33], v[26:29]
	ds_read_b128 v[30:33], v184 offset:39296
	ds_read_b128 v[34:37], v184 offset:39360
	s_waitcnt lgkmcnt(1)
	v_mfma_f32_16x16x32_bf16 v[26:29], v[4:7], v[30:33], v[26:29]
	s_waitcnt lgkmcnt(0)
	v_mfma_f32_16x16x32_bf16 v[26:29], v[0:3], v[34:37], v[26:29]
	ds_read_b128 v[30:33], v184 offset:43520
	ds_read_b128 v[34:37], v184 offset:43584
	s_waitcnt lgkmcnt(1)
	v_mfma_f32_16x16x32_bf16 v[30:33], v[12:15], v[30:33], 0
	s_waitcnt lgkmcnt(0)
	v_mfma_f32_16x16x32_bf16 v[30:33], v[8:11], v[34:37], v[30:33]
	ds_read_b128 v[34:37], v184 offset:43648
	ds_read_b128 v[38:41], v184 offset:43712
	s_waitcnt lgkmcnt(1)
	v_mfma_f32_16x16x32_bf16 v[30:33], v[4:7], v[34:37], v[30:33]
	s_waitcnt lgkmcnt(0)
	v_mfma_f32_16x16x32_bf16 v[30:33], v[0:3], v[38:41], v[30:33]
	ds_read_b128 v[34:37], v184 offset:47872
	ds_read_b128 v[38:41], v184 offset:47936
	s_waitcnt lgkmcnt(1)
	v_mfma_f32_16x16x32_bf16 v[34:37], v[12:15], v[34:37], 0
	s_waitcnt lgkmcnt(0)
	v_mfma_f32_16x16x32_bf16 v[34:37], v[8:11], v[38:41], v[34:37]
	ds_read_b128 v[38:41], v184 offset:48000
	ds_read_b128 v[42:45], v184 offset:48064
	s_waitcnt lgkmcnt(1)
	v_mfma_f32_16x16x32_bf16 v[34:37], v[4:7], v[38:41], v[34:37]
	s_waitcnt lgkmcnt(0)
	v_mfma_f32_16x16x32_bf16 v[34:37], v[0:3], v[42:45], v[34:37]
	ds_read_b128 v[38:41], v184 offset:52224
	ds_read_b128 v[42:45], v184 offset:52288
	s_waitcnt lgkmcnt(1)
	v_mfma_f32_16x16x32_bf16 v[38:41], v[12:15], v[38:41], 0
	s_waitcnt lgkmcnt(0)
	v_mfma_f32_16x16x32_bf16 v[38:41], v[8:11], v[42:45], v[38:41]
	ds_read_b128 v[42:45], v184 offset:52352
	ds_read_b128 v[46:49], v184 offset:52416
	s_waitcnt lgkmcnt(1)
	v_mfma_f32_16x16x32_bf16 v[38:41], v[4:7], v[42:45], v[38:41]
	s_waitcnt lgkmcnt(0)
	v_mfma_f32_16x16x32_bf16 v[38:41], v[0:3], v[46:49], v[38:41]
	ds_read_b128 v[42:45], v184 offset:56576
	ds_read_b128 v[46:49], v184 offset:56640
	s_waitcnt lgkmcnt(1)
	v_mfma_f32_16x16x32_bf16 v[42:45], v[12:15], v[42:45], 0
	s_waitcnt lgkmcnt(0)
	v_mfma_f32_16x16x32_bf16 v[42:45], v[8:11], v[46:49], v[42:45]
	ds_read_b128 v[46:49], v184 offset:56704
	ds_read_b128 v[50:53], v184 offset:56768
	s_waitcnt lgkmcnt(1)
	v_mfma_f32_16x16x32_bf16 v[42:45], v[4:7], v[46:49], v[42:45]
	s_waitcnt lgkmcnt(0)
	v_mfma_f32_16x16x32_bf16 v[42:45], v[0:3], v[50:53], v[42:45]
	ds_read_b128 v[46:49], v184 offset:60928
	ds_read_b128 v[50:53], v184 offset:60992
	s_waitcnt lgkmcnt(1)
	v_mfma_f32_16x16x32_bf16 v[46:49], v[12:15], v[46:49], 0
	s_waitcnt lgkmcnt(0)
	v_mfma_f32_16x16x32_bf16 v[46:49], v[8:11], v[50:53], v[46:49]
	ds_read_b128 v[50:53], v184 offset:61056
	ds_read_b128 v[54:57], v184 offset:61120
	s_waitcnt lgkmcnt(1)
	v_mfma_f32_16x16x32_bf16 v[46:49], v[4:7], v[50:53], v[46:49]
	s_waitcnt lgkmcnt(0)
	v_mfma_f32_16x16x32_bf16 v[46:49], v[0:3], v[54:57], v[46:49]
	ds_read_b128 v[50:53], v184 offset:65280
	ds_read_b128 v[54:57], v184 offset:65344
	s_waitcnt lgkmcnt(1)
	v_mfma_f32_16x16x32_bf16 v[12:15], v[12:15], v[50:53], 0
	s_waitcnt lgkmcnt(0)
	v_mfma_f32_16x16x32_bf16 v[8:11], v[8:11], v[54:57], v[12:15]
	s_nop 5
	ds_read_b128 v[12:15], v184 offset:65408
	ds_read_b128 v[50:53], v184 offset:65472
	s_waitcnt lgkmcnt(1)
	v_mfma_f32_16x16x32_bf16 v[4:7], v[4:7], v[12:15], v[8:11]
	s_waitcnt lgkmcnt(0)
	v_mfma_f32_16x16x32_bf16 v[0:3], v[0:3], v[50:53], v[4:7]
	s_nop 7
	s_mov_b32 s40, 0
	v_ashrrev_i32_e32 v4, 31, v3
	v_bitop3_b32 v3, v3, v4, v217 bitop3:0x1e
	v_and_or_b32 v3, v3, s67, v178
	v_ashrrev_i32_e32 v4, 31, v49
	v_bitop3_b32 v4, v49, v4, v217 bitop3:0x1e
	v_and_or_b32 v49, v4, s67, v177
	v_ashrrev_i32_e32 v4, 31, v45
	v_bitop3_b32 v4, v45, v4, v217 bitop3:0x1e
	v_and_or_b32 v45, v4, s67, v176
	v_ashrrev_i32_e32 v4, 31, v41
	v_bitop3_b32 v4, v41, v4, v217 bitop3:0x1e
	v_and_or_b32 v41, v4, s67, v175
	v_ashrrev_i32_e32 v4, 31, v37
	v_bitop3_b32 v4, v37, v4, v217 bitop3:0x1e
	v_and_or_b32 v37, v4, s67, v170
	v_ashrrev_i32_e32 v4, 31, v33
	v_bitop3_b32 v4, v33, v4, v217 bitop3:0x1e
	v_and_or_b32 v50, v4, s67, v181
	v_ashrrev_i32_e32 v4, 31, v29
	v_bitop3_b32 v4, v29, v4, v217 bitop3:0x1e
	v_and_or_b32 v51, v4, s67, v180
	v_ashrrev_i32_e32 v4, 31, v25
	v_bitop3_b32 v4, v25, v4, v217 bitop3:0x1e
	v_and_or_b32 v52, v4, s67, v179
	v_ashrrev_i32_e32 v4, 31, v2
	v_bitop3_b32 v2, v2, v4, v217 bitop3:0x1e
	v_and_or_b32 v2, v2, s67, v178
	v_ashrrev_i32_e32 v4, 31, v48
	v_bitop3_b32 v4, v48, v4, v217 bitop3:0x1e
	v_and_or_b32 v29, v4, s67, v177
	v_ashrrev_i32_e32 v4, 31, v44
	v_bitop3_b32 v4, v44, v4, v217 bitop3:0x1e
	v_and_or_b32 v33, v4, s67, v176
	v_ashrrev_i32_e32 v4, 31, v40
	v_bitop3_b32 v4, v40, v4, v217 bitop3:0x1e
	v_and_or_b32 v40, v4, s67, v175
	v_ashrrev_i32_e32 v4, 31, v36
	v_bitop3_b32 v4, v36, v4, v217 bitop3:0x1e
	v_and_or_b32 v36, v4, s67, v170
	v_ashrrev_i32_e32 v4, 31, v32
	v_bitop3_b32 v4, v32, v4, v217 bitop3:0x1e
	v_and_or_b32 v32, v4, s67, v181
	v_ashrrev_i32_e32 v4, 31, v28
	v_bitop3_b32 v4, v28, v4, v217 bitop3:0x1e
	v_and_or_b32 v28, v4, s67, v180
	v_ashrrev_i32_e32 v4, 31, v24
	v_bitop3_b32 v4, v24, v4, v217 bitop3:0x1e
	v_and_or_b32 v44, v4, s67, v179
	v_ashrrev_i32_e32 v4, 31, v1
	v_bitop3_b32 v1, v1, v4, v217 bitop3:0x1e
	v_and_or_b32 v1, v1, s67, v178
	v_ashrrev_i32_e32 v4, 31, v47
	v_bitop3_b32 v4, v47, v4, v217 bitop3:0x1e
	v_and_or_b32 v12, v4, s67, v177
	v_ashrrev_i32_e32 v4, 31, v43
	v_bitop3_b32 v4, v43, v4, v217 bitop3:0x1e
	v_and_or_b32 v13, v4, s67, v176
	v_ashrrev_i32_e32 v4, 31, v39
	v_bitop3_b32 v4, v39, v4, v217 bitop3:0x1e
	v_and_or_b32 v14, v4, s67, v175
	v_ashrrev_i32_e32 v4, 31, v35
	v_bitop3_b32 v4, v35, v4, v217 bitop3:0x1e
	v_and_or_b32 v15, v4, s67, v170
	v_max_u32_e32 v35, v41, v45
	v_ashrrev_i32_e32 v4, 31, v31
	v_bitop3_b32 v4, v31, v4, v217 bitop3:0x1e
	v_and_or_b32 v24, v4, s67, v181
	v_max_u32_e32 v31, v29, v2
	v_ashrrev_i32_e32 v4, 31, v27
	v_bitop3_b32 v4, v27, v4, v217 bitop3:0x1e
	v_and_or_b32 v25, v4, s67, v180
	v_min_u32_e32 v2, v29, v2
	v_ashrrev_i32_e32 v4, 31, v23
	v_bitop3_b32 v4, v23, v4, v217 bitop3:0x1e
	v_and_or_b32 v23, v4, s67, v179
	v_ashrrev_i32_e32 v4, 31, v0
	v_bitop3_b32 v0, v0, v4, v217 bitop3:0x1e
	v_and_or_b32 v0, v0, s67, v178
	v_ashrrev_i32_e32 v4, 31, v46
	v_bitop3_b32 v4, v46, v4, v217 bitop3:0x1e
	v_and_or_b32 v4, v4, s67, v177
	v_ashrrev_i32_e32 v5, 31, v42
	v_bitop3_b32 v5, v42, v5, v217 bitop3:0x1e
	v_and_or_b32 v5, v5, s67, v176
	v_ashrrev_i32_e32 v6, 31, v38
	v_bitop3_b32 v6, v38, v6, v217 bitop3:0x1e
	v_and_or_b32 v6, v6, s67, v175
	v_ashrrev_i32_e32 v7, 31, v34
	v_bitop3_b32 v7, v34, v7, v217 bitop3:0x1e
	v_and_or_b32 v7, v7, s67, v170
	v_ashrrev_i32_e32 v8, 31, v30
	v_bitop3_b32 v8, v30, v8, v217 bitop3:0x1e
	v_and_or_b32 v8, v8, s67, v181
	v_ashrrev_i32_e32 v9, 31, v26
	v_bitop3_b32 v9, v26, v9, v217 bitop3:0x1e
	v_and_or_b32 v9, v9, s67, v180
	v_ashrrev_i32_e32 v10, 31, v22
	v_bitop3_b32 v10, v22, v10, v217 bitop3:0x1e
	v_and_or_b32 v10, v10, s67, v179
	v_max_u32_e32 v11, v10, v9
	v_min_u32_e32 v9, v10, v9
	v_max_u32_e32 v10, v8, v7
	v_min_u32_e32 v7, v8, v7
	v_max_u32_e32 v8, v6, v5
	v_min_u32_e32 v5, v6, v5
	v_max_u32_e32 v6, v4, v0
	v_min_u32_e32 v0, v4, v0
	v_max_u32_e32 v22, v11, v10
	v_min_u32_e32 v4, v11, v10
	v_max_u32_e32 v10, v9, v7
	v_min_u32_e32 v7, v9, v7
	v_max_u32_e32 v9, v8, v6
	v_min_u32_e32 v6, v8, v6
	v_max_u32_e32 v8, v5, v0
	v_min_u32_e32 v0, v5, v0
	v_max_u32_e32 v5, v10, v4
	v_min_u32_e32 v10, v10, v4
	v_max_u32_e32 v11, v8, v6
	v_min_u32_e32 v6, v8, v6
	v_max_u32_e32 v80, v22, v9
	v_min_u32_e32 v8, v22, v9
	v_max_u32_e32 v9, v5, v11
	v_min_u32_e32 v11, v5, v11
	v_max_u32_e32 v22, v10, v6
	v_min_u32_e32 v26, v10, v6
	v_max_u32_e32 v6, v7, v0
	v_min_u32_e32 v87, v7, v0
	v_max_u32_e32 v0, v22, v8
	v_min_u32_e32 v10, v22, v8
	v_max_u32_e32 v22, v6, v11
	v_min_u32_e32 v11, v6, v11
	v_max_u32_e32 v81, v9, v0
	v_min_u32_e32 v82, v9, v0
	v_max_u32_e32 v83, v22, v10
	v_min_u32_e32 v84, v22, v10
	v_max_u32_e32 v0, v23, v25
	v_min_u32_e32 v22, v23, v25
	v_max_u32_e32 v23, v24, v15
	v_min_u32_e32 v15, v24, v15
	v_max_u32_e32 v24, v14, v13
	v_min_u32_e32 v13, v14, v13
	v_max_u32_e32 v14, v12, v1
	v_min_u32_e32 v1, v12, v1
	v_max_u32_e32 v25, v0, v23
	v_min_u32_e32 v0, v0, v23
	v_max_u32_e32 v12, v22, v15
	v_min_u32_e32 v15, v22, v15
	v_max_u32_e32 v22, v24, v14
	v_min_u32_e32 v14, v24, v14
	v_max_u32_e32 v23, v13, v1
	v_min_u32_e32 v1, v13, v1
	v_max_u32_e32 v13, v12, v0
	v_min_u32_e32 v0, v12, v0
	v_max_u32_e32 v24, v23, v14
	v_min_u32_e32 v14, v23, v14
	v_max_u32_e32 v72, v25, v22
	v_min_u32_e32 v22, v25, v22
	v_max_u32_e32 v23, v13, v24
	v_min_u32_e32 v24, v13, v24
	v_max_u32_e32 v25, v0, v14
	v_min_u32_e32 v0, v0, v14
	v_max_u32_e32 v14, v15, v1
	v_max_u32_e32 v85, v11, v26
	v_min_u32_e32 v86, v11, v26
	v_min_u32_e32 v79, v15, v1
	v_max_u32_e32 v1, v25, v22
	v_min_u32_e32 v25, v25, v22
	v_max_u32_e32 v26, v14, v24
	v_min_u32_e32 v27, v14, v24
	v_max_u32_e32 v73, v23, v1
	v_min_u32_e32 v74, v23, v1
	v_max_u32_e32 v75, v26, v25
	v_min_u32_e32 v76, v26, v25
	v_max_u32_e32 v77, v27, v0
	v_min_u32_e32 v78, v27, v0
	v_max_u32_e32 v0, v44, v28
	v_min_u32_e32 v1, v44, v28
	v_max_u32_e32 v26, v32, v36
	v_min_u32_e32 v27, v32, v36
	v_max_u32_e32 v28, v40, v33
	v_min_u32_e32 v30, v40, v33
	v_max_u32_e32 v29, v0, v26
	v_min_u32_e32 v0, v0, v26
	v_max_u32_e32 v26, v1, v27
	v_min_u32_e32 v1, v1, v27
	v_max_u32_e32 v27, v28, v31
	v_min_u32_e32 v28, v28, v31
	v_max_u32_e32 v31, v30, v2
	v_min_u32_e32 v2, v30, v2
	v_max_u32_e32 v30, v26, v0
	v_min_u32_e32 v0, v26, v0
	v_max_u32_e32 v32, v31, v28
	v_min_u32_e32 v28, v31, v28
	v_max_u32_e32 v88, v29, v27
	v_min_u32_e32 v29, v29, v27
	v_max_u32_e32 v31, v30, v32
	v_min_u32_e32 v30, v30, v32
	v_max_u32_e32 v32, v0, v28
	v_min_u32_e32 v0, v0, v28
	v_max_u32_e32 v28, v1, v2
	v_min_u32_e32 v95, v1, v2
	v_max_u32_e32 v1, v32, v29
	v_min_u32_e32 v2, v32, v29
	v_max_u32_e32 v32, v28, v30
	v_min_u32_e32 v33, v28, v30
	v_max_u32_e32 v89, v31, v1
	v_min_u32_e32 v90, v31, v1
	v_max_u32_e32 v91, v32, v2
	v_min_u32_e32 v92, v32, v2
	v_max_u32_e32 v93, v33, v0
	v_min_u32_e32 v94, v33, v0
	v_max_u32_e32 v0, v52, v51
	v_min_u32_e32 v1, v52, v51
	v_max_u32_e32 v2, v50, v37
	v_min_u32_e32 v34, v50, v37
	v_min_u32_e32 v36, v41, v45
	v_max_u32_e32 v37, v49, v3
	v_min_u32_e32 v3, v49, v3
	v_max_u32_e32 v38, v0, v2
	v_min_u32_e32 v0, v0, v2
	v_max_u32_e32 v2, v1, v34
	v_min_u32_e32 v1, v1, v34
	v_max_u32_e32 v39, v35, v37
	v_min_u32_e32 v34, v35, v37
	v_max_u32_e32 v35, v36, v3
	v_min_u32_e32 v3, v36, v3
	v_max_u32_e32 v36, v2, v0
	v_min_u32_e32 v0, v2, v0
	v_max_u32_e32 v2, v35, v34
	v_min_u32_e32 v35, v35, v34
	v_max_u32_e32 v96, v38, v39
	v_min_u32_e32 v37, v38, v39
	v_max_u32_e32 v38, v36, v2
	v_min_u32_e32 v2, v36, v2
	v_max_u32_e32 v36, v0, v35
	v_max_u32_e32 v39, v1, v3
	v_min_u32_e32 v0, v0, v35
	v_min_u32_e32 v103, v1, v3
	v_max_u32_e32 v1, v36, v37
	v_min_u32_e32 v3, v36, v37
	v_max_u32_e32 v40, v39, v2
	v_min_u32_e32 v2, v39, v2
	v_max_u32_e32 v97, v38, v1
	v_min_u32_e32 v98, v38, v1
	v_max_u32_e32 v99, v40, v3
	v_min_u32_e32 v100, v40, v3
	v_max_u32_e32 v101, v2, v0
	v_min_u32_e32 v102, v2, v0
	v_mov_b32_e32 v0, 0
	v_mov_b32_e32 v1, 0
	v_mov_b32_e32 v2, 0
	v_mov_b32_e32 v3, 0
